# v36
# baseline (speedup 1.0000x reference)
_Z14fwd_megakernel6Params:
	s_load_dword s3, s[0:1], 0x150
	v_and_b32_e32 v1, 0x3ff, v0
	s_add_u32 s10, s0, 0x150
	v_readfirstlane_b32 s40, v1
	s_addc_u32 s11, s1, 0
	s_and_b32 s33, s40, 0xffffffc0
	s_cmp_ge_u32 s33, 0x100
	s_cbranch_scc0 .Lprio_entry
	s_setprio 1
.Lprio_entry:
	s_getreg_b32 s4, hwreg(HW_REG_XCC_ID, 0, 4)
	v_mbcnt_lo_u32_b32 v2, -1, 0
	v_mbcnt_hi_u32_b32 v2, -1, v2
	s_and_b32 s36, s4, 15
	v_or_b32_e32 v2, s33, v2
	v_cmp_eq_u32_e32 vcc, 0, v2
	s_and_saveexec_b64 s[4:5], vcc
	s_cbranch_execz .LBB0_3
	s_mov_b64 s[6:7], exec
	v_mbcnt_lo_u32_b32 v2, s6, 0
	v_mbcnt_hi_u32_b32 v2, s7, v2
	v_cmp_eq_u32_e32 vcc, 0, v2
	s_and_b64 s[8:9], exec, vcc
	s_mov_b64 exec, s[8:9]
	s_cbranch_execz .LBB0_3
	s_load_dwordx2 s[8:9], s[0:1], 0x148
	s_lshl_b32 s12, s36, 8
	v_mov_b32_e32 v2, 0x9802000
	s_waitcnt lgkmcnt(0)
	s_add_u32 s8, s8, s12
	s_addc_u32 s9, s9, 0
	s_bcnt1_i32_b64 s6, s[6:7]
	v_mov_b32_e32 v3, s6
	global_atomic_add v2, v3, s[8:9] offset:256

.LBB0_468:
	s_or_b64 exec, exec, s[4:5]
	s_barrier
	s_setprio 0
	s_load_dwordx4 s[12:15], s[0:1], 0x140
	s_mov_b32 s17, s2
	v_mbcnt_lo_u32_b32 v0, -1, 0
	v_mbcnt_hi_u32_b32 v0, -1, v0
	s_cmpk_gt_i32 s17, 0xff
	s_cbranch_scc1 .LBB0_536
	v_or_b32_e32 v1, s33, v0
	v_and_b32_e32 v48, 63, v0
	s_load_dwordx2 s[24:25], s[0:1], 0x78
	v_ashrrev_i32_e32 v2, 6, v1
	v_bfe_u32 v49, v1, 7, 1
	s_mov_b32 s4, 0xa300
	v_mov_b32_e32 v51, 0
	v_lshlrev_b32_e32 v50, 1, v48
	s_waitcnt lgkmcnt(0)
	s_add_u32 s20, s14, 0x32000000
	v_mad_u32_u24 v72, v49, s4, 0
	v_bfe_u32 v4, v0, 5, 1
	v_and_b32_e32 v5, 31, v0
	v_and_b32_e32 v6, 1, v2
	v_lshl_add_u64 v[0:1], s[14:15], 0, v[50:51]
	s_mov_b64 s[4:5], 0xa000000
	s_addc_u32 s21, s15, 0
	v_lshlrev_b32_e32 v73, 3, v6
	v_lshl_add_u64 v[52:53], v[0:1], 0, s[4:5]
	v_lshlrev_b32_e32 v0, 7, v6
	v_mov_b32_e32 v1, v51
	s_add_u32 s22, s14, 0x12000000
	v_cmp_lt_i32_e32 vcc, 3, v2
	v_lshl_add_u64 v[0:1], s[12:13], 0, v[0:1]
	v_lshlrev_b32_e32 v2, 2, v5
	v_mov_b32_e32 v3, v51
	v_or_b32_e32 v78, 1, v73
	v_or_b32_e32 v80, 2, v73
	v_or_b32_e32 v82, 3, v73
	v_or_b32_e32 v84, 4, v73
	v_or_b32_e32 v86, 5, v73
	v_or_b32_e32 v88, 6, v73
	v_or_b32_e32 v90, 7, v73
	s_addc_u32 s23, s15, 0
	s_mov_b32 s27, 0
	v_cmp_eq_u32_e64 s[10:11], 1, v6
	v_cmp_eq_u32_e64 s[4:5], 0, v48
	v_lshlrev_b32_e32 v74, 2, v4
	v_lshl_or_b32 v75, v6, 5, v5
	v_cmp_gt_u32_e64 s[6:7], 32, v48
	v_lshl_add_u64 v[54:55], v[0:1], 0, v[2:3]
	v_lshlrev_b32_e32 v76, 4, v4
	v_xor_b32_e32 v77, 0x7ff, v73
	v_xor_b32_e32 v79, 0x7fe, v73
	v_xor_b32_e32 v81, 0x7fd, v73
	v_xor_b32_e32 v83, 0x7fc, v73
	v_xor_b32_e32 v85, 0x7fb, v73
	v_xor_b32_e32 v87, 0x7fa, v73
	v_xor_b32_e32 v89, 0x7f9, v73
	v_xor_b32_e32 v91, 0x7f8, v73
	v_mul_u32_u24_e32 v92, 0x2800, v6
	v_lshlrev_b32_e32 v93, 6, v6
	v_mul_u32_u24_e32 v94, 0x500, v78
	v_lshlrev_b32_e32 v95, 3, v78
	v_lshlrev_b32_e32 v96, 3, v80
	v_lshlrev_b32_e32 v97, 3, v82
	v_lshlrev_b32_e32 v98, 3, v84
	v_lshlrev_b32_e32 v99, 3, v86
	v_lshlrev_b32_e32 v100, 3, v88
	v_lshlrev_b32_e32 v101, 3, v90
	v_lshl_add_u64 v[56:57], s[20:21], 0, v[50:51]
	v_lshl_or_b32 v102, v4, 6, v5
	v_sub_u32_e32 v103, 0, v73
	s_movk_i32 s36, 0x1400
	s_movk_i32 s37, 0xc00
	s_mov_b32 s38, 0x5040100
	v_lshlrev_b32_e32 v58, 1, v48
	v_mbcnt_hi_u32_b32 v104, -1, v160

.LBB0_551:
	s_or_b64 exec, exec, s[4:5]
	s_mov_b32 s8, s2
	s_barrier
	s_cmp_ge_u32 s33, 0x100
	s_cbranch_scc0 .Lprio_post
	s_setprio 1
.Lprio_post:
	s_load_dwordx4 s[4:7], s[0:1], 0x140
	v_mbcnt_lo_u32_b32 v25, -1, 0
	v_mbcnt_hi_u32_b32 v25, -1, v25
	v_mbcnt_lo_u32_b32 v0, -1, 0
	v_mbcnt_hi_u32_b32 v0, -1, v0
	s_nop 0
	v_or_b32_e32 v0, s40, v0
	v_ashrrev_i32_e32 v0, 6, v0
	v_lshl_add_u32 v24, s8, 3, v0
	s_mov_b32 s8, 0x10000
	v_cmp_gt_i32_e32 vcc, s8, v24
	s_and_saveexec_b64 s[8:9], vcc
	s_cbranch_execz .LBB0_554
	s_load_dwordx2 s[10:11], s[0:1], 0x88
	s_load_dwordx4 s[12:15], s[0:1], 0x78
	v_lshlrev_b32_e32 v0, 5, v25
	v_and_b32_e32 v26, 0x7e0, v0
	v_and_b32_e32 v34, 63, v25
	v_mov_b32_e32 v27, 0
	s_waitcnt lgkmcnt(0)
	global_load_dwordx4 v[0:3], v26, s[10:11]
	global_load_dwordx4 v[4:7], v26, s[10:11] offset:16
	global_load_dwordx4 v[8:11], v26, s[12:13] offset:16
	global_load_dwordx4 v[12:15], v26, s[14:15] offset:16
	global_load_dwordx4 v[16:19], v26, s[12:13]
	global_load_dwordx4 v[20:23], v26, s[14:15]
	s_add_u32 s10, s6, 0x2a000000
	v_ashrrev_i32_e32 v25, 31, v24
	s_movk_i32 s17, 0x1400
	v_mov_b64_e32 v[30:31], s[6:7]
	s_movk_i32 s27, 0xc00
	s_addc_u32 s11, s7, 0
	v_lshlrev_b32_e32 v26, 4, v34
	v_mad_i64_i32 v[28:29], s[22:23], v24, s17, v[30:31]
	s_ashr_i32 s17, s16, 31
	v_mad_i64_i32 v[30:31], s[22:23], v24, s27, v[30:31]
	v_lshlrev_b64 v[32:33], 11, v[24:25]
	v_lshlrev_b32_e32 v36, 5, v34
	v_mov_b32_e32 v37, v27
	s_mul_hi_i32 s13, s16, 0x1400
	s_mul_i32 s12, s16, 0x1400
	s_mov_b64 s[14:15], 0
	s_mov_b64 s[20:21], 0x8000000
	s_mov_b32 s24, 0x12000000
	s_mov_b32 s25, 0x12001000
	v_mov_b32_e32 v52, 0x358637bd
	s_mov_b32 s26, 0x800000
	s_lshl_b64 s[22:23], s[16:17], 11
	v_or_b32_e32 v34, v32, v26
	v_mov_b32_e32 v35, v33
	v_lshl_add_u64 v[36:37], s[4:5], 0, v[36:37]
	s_mov_b32 s17, 0xffff
	s_waitcnt vmcnt(5)
	v_mov_b32_e32 v38, v1
	v_mov_b32_e32 v40, v3
	s_waitcnt vmcnt(4)
	v_mov_b32_e32 v42, v5
	v_mov_b32_e32 v44, v7
